# v024 + down-projection GEMM walks row tiles in descending order (recently written HID rows first)
# baseline (speedup 1.0000x reference)
.LBB0_1423:
	s_andn2_b64 vcc, exec, s[2:3]
	s_cbranch_vccnz .LBB0_1506
	s_and_b64 s[0:1], s[20:21], exec
	s_cselect_b32 s1, s50, 64
	s_cselect_b32 s0, s49, 16
	s_cselect_b32 s42, 0, 0x80
	s_cmp_lt_u32 s73, s1
	v_readlane_b32 s6, v254, 17
	s_cselect_b64 s[2:3], -1, 0
	v_readlane_b32 s7, v254, 18
	s_and_b64 s[6:7], s[6:7], s[2:3]
	s_mov_b32 s4, s96
	v_cndmask_b32_e64 v0, 0, 1, s[6:7]
	v_cmp_ne_u32_e64 s[2:3], 1, v0
	s_andn2_b64 vcc, exec, s[6:7]
	v_mbcnt_lo_u32_b32 v10, -1, 0
	v_mbcnt_hi_u32_b32 v10, -1, v10
	s_cbranch_vccnz .LBB0_1426
	s_lshr_b32 s5, s1, 3
	v_readlane_b32 s6, v254, 24
	s_mul_i32 s5, s5, s6
	v_readlane_b32 s6, v254, 19
	s_add_i32 s5, s5, s6
	s_lshr_b32 s6, s5, 2
	s_and_b32 s6, s6, 0x1ffffff8
	s_sub_i32 s7, s0, s6
	s_min_i32 s7, s7, 8
	s_abs_i32 s8, s7
	v_cvt_f32_u32_e32 v0, s8
	s_sub_i32 s10, 0, s8
	s_and_b32 s5, s5, 31
	s_add_i32 s6, s6, s42
	v_rcp_iflag_f32_e32 v0, v0
	s_ashr_i32 s9, s7, 31
	v_mul_f32_e32 v0, 0x4f7ffffe, v0
	v_cvt_u32_f32_e32 v0, v0
	s_nop 0
	v_readfirstlane_b32 s11, v0
	s_mul_i32 s10, s10, s11
	s_mul_hi_u32 s10, s11, s10
	s_add_i32 s11, s11, s10
	s_mul_hi_u32 s10, s5, s11
	s_mul_i32 s11, s10, s8
	s_sub_i32 s11, s5, s11
	s_add_i32 s12, s10, 1
	s_sub_i32 s13, s11, s8
	s_cmp_ge_u32 s11, s8
	s_cselect_b32 s10, s12, s10
	s_cselect_b32 s11, s13, s11
	s_add_i32 s12, s10, 1
	s_cmp_ge_u32 s11, s8
	s_cselect_b32 s8, s12, s10
	s_xor_b32 s8, s8, s9
	s_sub_i32 s36, s8, s9
	s_mul_i32 s7, s36, s7
	s_sub_i32 s5, s5, s7
	s_add_i32 s65, s6, s5
	s_lshl_b32 s5, s42, 1
	s_add_i32 s5, s5, s0
	s_add_i32 s5, s5, -1
	s_sub_i32 s65, s5, s65

.LBB0_1432:
	s_andn2_b64 vcc, exec, s[74:75]
	s_add_i32 s60, s60, 1
	s_cbranch_vccnz .LBB0_1435
	s_mul_i32 s4, s60, s47
	s_add_i32 s4, s4, s73
	s_cmp_ge_i32 s4, s1
	s_mov_b64 s[26:27], 0
	s_cbranch_scc1 .LBB0_1436
	s_ashr_i32 s5, s4, 31
	s_lshr_b32 s5, s5, 29
	s_add_i32 s5, s4, s5
	s_ashr_i32 s26, s5, 3
	s_and_b32 s5, s5, -8
	s_sub_i32 s4, s4, s5
	s_lshr_b32 s5, s4, 31
	s_or_b32 s5, s62, s5
	s_mul_i32 s4, s4, s5
	s_add_i32 s4, s4, s26
	s_ashr_i32 s5, s4, 31
	s_lshr_b32 s5, s5, 27
	s_add_i32 s5, s4, s5
	s_ashr_i32 s26, s5, 5
	s_lshl_b32 s26, s26, 3
	s_sub_i32 s27, s0, s26
	s_min_i32 s27, s27, 8
	s_abs_i32 s28, s27
	v_cvt_f32_u32_e32 v2, s28
	s_sub_i32 s38, 0, s28
	s_andn2_b32 s5, s5, 31
	s_sub_i32 s4, s4, s5
	v_rcp_iflag_f32_e32 v2, v2
	s_abs_i32 s5, s4
	s_xor_b32 s29, s4, s27
	s_ashr_i32 s29, s29, 31
	v_mul_f32_e32 v2, 0x4f7ffffe, v2
	v_cvt_u32_f32_e32 v2, v2
	s_nop 0
	v_readfirstlane_b32 s39, v2
	s_mul_i32 s38, s38, s39
	s_mul_hi_u32 s38, s39, s38
	s_add_i32 s39, s39, s38
	s_mul_hi_u32 s38, s5, s39
	s_mul_i32 s39, s38, s28
	s_sub_i32 s5, s5, s39
	s_add_i32 s40, s38, 1
	s_sub_i32 s39, s5, s28
	s_cmp_ge_u32 s5, s28
	s_cselect_b32 s38, s40, s38
	s_cselect_b32 s5, s39, s5
	s_add_i32 s39, s38, 1
	s_cmp_ge_u32 s5, s28
	s_cselect_b32 s5, s39, s38
	s_xor_b32 s5, s5, s29
	s_sub_i32 s63, s5, s29
	s_mul_i32 s5, s63, s27
	s_sub_i32 s4, s4, s5
	s_add_i32 s4, s4, s42
	s_add_i32 s64, s4, s26
	s_lshl_b32 s4, s42, 1
	s_add_i32 s4, s4, s0
	s_add_i32 s4, s4, -1
	s_sub_i32 s64, s4, s64
	s_mov_b64 s[26:27], -1
	s_branch .LBB0_1436
